# P6 third items: prompt items on waves 0-5 of every workgroup, the 176 sample items one per workgroup on wave 6
# baseline (speedup 1.0000x reference)
; __global__ void __launch_bounds__(512, 2) fwd_kernel(Args args) {
;     ...
;         for (int it = gw; it < 264 * 22; it += NGW) act_item(it, UP, HALO, args.in[I_SCONV], args.in[I_WCONV], args.in[I_BCONV], out, lane);
.LBB0_770:
	s_add_i32 s80, s80, s96
	s_cmpk_gt_i32 s80, 0x17ff
	s_cbranch_scc1 .LBB0_819
	v_add_u32_e32 v43, s70, v43
	s_cmpk_lt_i32 s80, 0x1000
	s_cbranch_scc1 .LBB0_771
	v_readlane_b32 s0, v237, 12
	s_mul_i32 s1, s2, 6
	s_nop 0
	s_cmp_gt_u32 s0, 5
	s_cbranch_scc1 .Lp6_w67
	s_add_i32 s1, s1, s0
	s_addk_i32 s1, 0x1000
	s_branch .Lp6_remap
.Lp6_w67:
	s_cmp_gt_u32 s0, 6
	s_cbranch_scc1 .LBB0_819
	s_cmpk_gt_u32 s2, 0xaf
	s_cbranch_scc1 .LBB0_819
	s_add_i32 s1, s2, 0x1600
.Lp6_remap:
	s_sub_i32 s0, s1, s80
	s_lshl_b32 s0, s0, 7
	v_add_u32_e32 v43, s0, v43
	s_mov_b32 s80, s1
